# v22 + same unit-boundary treatment for the P4 GEMM loop (peel, SrcC=0, hoisted As11 loads, back-edge barrier)
# baseline (speedup 1.0000x reference)
; #define PG8_STAGE(bufoff, gbase, voff) do { _Pragma("unroll") for (int _i = 0; _i < 2; ++_i) \
;         __builtin_amdgcn_global_load_lds((const unsigned*)((const char*)(gbase) + (voff)[_i]), (PG8_LAS unsigned*)(lds + (bufoff) + ldsw + _i * 8192), 16, 0, 0); } while (0)
; #define PG8_LDA(dst, b, h) do { _Pragma("unroll") for (int m = 0; m < 4; ++m) _Pragma("unroll") for (int k = 0; k < 2; ++k) dst[m][k] = *(const PG8_LAS bf16x8*)(lds + PG8_SA(b, h) + aoff + m * 2048 + k * 1024); } while (0)
; #define PG8_LDB(dst, b, h) do { _Pragma("unroll") for (int n = 0; n < 2; ++n) _Pragma("unroll") for (int k = 0; k < 2; ++k) dst[n][k] = *(const PG8_LAS bf16x8*)(lds + PG8_SB(b, h) + boff + n * 2048 + k * 1024); } while (0)
; #define PG8_WAIT_V(n) asm volatile("s_waitcnt vmcnt(" #n ")" ::: "memory")
; #define PG8_WAIT_L(n) asm volatile("s_waitcnt lgkmcnt(" #n ")" ::: "memory")
; #define PG8_BAR __builtin_amdgcn_s_barrier()
; template <class Epi, class Sched, bool ALIGN_EPI = false, bool SP2 = false>
; __device__ __forceinline__ void gemm_phase(PG8_LAS unsigned char* lds, const Gemm g, const Sched& S, const Epi& E) {
;     ...
;         const bool has_next = S.next(ui + 1, nxt);
;         const char* nA = has_next ? (const char*)g.A + (size_t)nxt.pm * tstep : cA; const char* nB = has_next ? (const char*)g.Bt + (size_t)nxt.pn * tstep : cB;
;         for (int t = 0; t < nt; t += 2) {
;             const bool last = (t == nt - 2);
;             const char* a1 = cA + (size_t)(t + 1) * kstep;
;             const char* a2 = last ? nA : cA + (size_t)(t + 2) * kstep; const char* b2 = last ? nB : cB + (size_t)(t + 2) * kstep;
;             const char* a3 = a2 + kstep; const char* b3 = b2 + kstep;
;             if (last && has_next) S.a_ready(nxt);
;             if constexpr (SP2) {
;             PG8_LDB(B0, 0, 0); PG8_LDB(B1, 0, 1); PG8_SCHED; PG8_LDA(At, 0, 0); PG8_STAGE(PG8_SA(1, 1), a1 + hstep, voffA);
;             PG8_WAIT_V(8); PG8_WAIT_L(0); PG8_BAR; PG8_MMA(0, 0, At, B0); PG8_MMA(0, 1, At, B1); PG8_BAR; PG8_SCHED;
;     ...
; #pragma unroll
;         for (int a = 0; a < 2; ++a)
; #pragma unroll
;             for (int b = 0; b < 2; ++b)
; #pragma unroll
;                 for (int m = 0; m < 4; ++m)
; #pragma unroll
;                     for (int n = 0; n < 2; ++n) acc[a][b][m][n] = (f32x4){0.f, 0.f, 0.f, 0.f};
;         cur = nxt; cA = nA; cB = nB; ++ui;
.LBB0_456:
	s_ashr_i32 s25, s24, 31
	s_lshl_b64 s[26:27], s[24:25], 19
	s_add_u32 s26, s33, s26
	s_addc_u32 s27, s42, s27
	s_and_b64 s[28:29], s[0:1], exec
	s_cselect_b32 s25, s27, s35
	s_cselect_b32 s61, s26, s34
	s_ashr_i32 s21, s20, 31
	s_lshl_b64 s[28:29], s[20:21], 19
	s_add_u32 s28, s43, s28
	s_addc_u32 s29, s44, s29
	s_and_b64 s[38:39], s[0:1], exec
	s_cselect_b32 s21, s29, s41
	s_cselect_b32 s62, s28, s40
	s_add_u32 s34, s34, 0x40080
	s_addc_u32 s35, s35, 0
	s_add_u32 s63, s40, 0x100
	v_mov_b32_e32 v0, 0
	s_addc_u32 s64, s41, 0
	s_mov_b32 s65, -2
	v_mov_b32_e32 v1, v0
	s_cmp_lg_u32 s51, 1
	s_cbranch_scc1 .Lp4_peel
	v_mov_b32_e32 v2, v0
	v_mov_b32_e32 v3, v0
	v_mov_b32_e32 v4, v0
	v_mov_b32_e32 v5, v0
	v_mov_b32_e32 v6, v0
	v_mov_b32_e32 v7, v0
	v_mov_b32_e32 v8, v0
	v_mov_b32_e32 v9, v0
	v_mov_b32_e32 v10, v0
	v_mov_b32_e32 v11, v0
	v_mov_b32_e32 v16, v0
	v_mov_b32_e32 v17, v0
	v_mov_b32_e32 v18, v0
	v_mov_b32_e32 v19, v0
	v_mov_b32_e32 v28, v0
	v_mov_b32_e32 v29, v0
	v_mov_b32_e32 v30, v0
	v_mov_b32_e32 v31, v0
	v_mov_b32_e32 v32, v0
	v_mov_b32_e32 v33, v0
	v_mov_b32_e32 v34, v0
	v_mov_b32_e32 v35, v0
	v_mov_b32_e32 v40, v0
	v_mov_b32_e32 v41, v0
	v_mov_b32_e32 v42, v0
	v_mov_b32_e32 v43, v0
	v_mov_b32_e32 v44, v0
	v_mov_b32_e32 v45, v0
	v_mov_b32_e32 v46, v0
	v_mov_b32_e32 v47, v0
	v_mov_b32_e32 v12, v0
	v_mov_b32_e32 v13, v0
	v_mov_b32_e32 v14, v0
	v_mov_b32_e32 v15, v0
	v_mov_b32_e32 v20, v0
	v_mov_b32_e32 v21, v0
	v_mov_b32_e32 v22, v0
	v_mov_b32_e32 v23, v0
	v_mov_b32_e32 v24, v0
	v_mov_b32_e32 v25, v0
	v_mov_b32_e32 v26, v0
	v_mov_b32_e32 v27, v0
	v_mov_b32_e32 v36, v0
	v_mov_b32_e32 v37, v0
	v_mov_b32_e32 v38, v0
	v_mov_b32_e32 v39, v0
	v_mov_b32_e32 v48, v0
	v_mov_b32_e32 v49, v0
	v_mov_b32_e32 v50, v0
	v_mov_b32_e32 v51, v0
	v_mov_b32_e32 v52, v0
	v_mov_b32_e32 v53, v0
	v_mov_b32_e32 v54, v0
	v_mov_b32_e32 v55, v0
	v_mov_b32_e32 v56, v0
	v_mov_b32_e32 v57, v0
	v_mov_b32_e32 v58, v0
	v_mov_b32_e32 v59, v0
	v_mov_b32_e32 v60, v0
	v_mov_b32_e32 v61, v0
	v_mov_b32_e32 v62, v0
	v_mov_b32_e32 v63, v0
	v_mov_b32_e32 v64, v0
	v_mov_b32_e32 v65, v0
	v_mov_b32_e32 v66, v0
	v_mov_b32_e32 v67, v0
	v_mov_b32_e32 v68, v0
	v_mov_b32_e32 v69, v0
	v_mov_b32_e32 v70, v0
	v_mov_b32_e32 v71, v0
	v_mov_b32_e32 v72, v0
	v_mov_b32_e32 v73, v0
	v_mov_b32_e32 v74, v0
	v_mov_b32_e32 v75, v0
	v_mov_b32_e32 v80, v0
	v_mov_b32_e32 v81, v0
	v_mov_b32_e32 v82, v0
	v_mov_b32_e32 v83, v0
	v_mov_b32_e32 v92, v0
	v_mov_b32_e32 v93, v0
	v_mov_b32_e32 v94, v0
	v_mov_b32_e32 v95, v0
	v_mov_b32_e32 v100, v0
	v_mov_b32_e32 v101, v0
	v_mov_b32_e32 v102, v0
	v_mov_b32_e32 v103, v0
	v_mov_b32_e32 v104, v0
	v_mov_b32_e32 v105, v0
	v_mov_b32_e32 v106, v0
	v_mov_b32_e32 v107, v0
	v_mov_b32_e32 v108, v0
	v_mov_b32_e32 v109, v0
	v_mov_b32_e32 v110, v0
	v_mov_b32_e32 v111, v0
	v_mov_b32_e32 v76, v0
	v_mov_b32_e32 v77, v0
	v_mov_b32_e32 v78, v0
	v_mov_b32_e32 v79, v0
	v_mov_b32_e32 v84, v0
	v_mov_b32_e32 v85, v0
	v_mov_b32_e32 v86, v0
	v_mov_b32_e32 v87, v0
	v_mov_b32_e32 v88, v0
	v_mov_b32_e32 v89, v0
	v_mov_b32_e32 v90, v0
	v_mov_b32_e32 v91, v0
	v_mov_b32_e32 v96, v0
	v_mov_b32_e32 v97, v0
	v_mov_b32_e32 v98, v0
	v_mov_b32_e32 v99, v0
	v_mov_b32_e32 v112, v0
	v_mov_b32_e32 v113, v0
	v_mov_b32_e32 v114, v0
	v_mov_b32_e32 v115, v0
	v_mov_b32_e32 v116, v0
	v_mov_b32_e32 v117, v0
	v_mov_b32_e32 v118, v0
	v_mov_b32_e32 v119, v0
	v_mov_b32_e32 v120, v0
	v_mov_b32_e32 v121, v0
	v_mov_b32_e32 v122, v0
	v_mov_b32_e32 v123, v0
	v_mov_b32_e32 v124, v0
	v_mov_b32_e32 v125, v0
	v_mov_b32_e32 v126, v0
	v_mov_b32_e32 v127, v0
.LBB0_457:
	ds_read_b128 v[128:131], v169
	ds_read_b128 v[132:135], v169 offset:1024
	ds_read_b128 v[136:139], v169 offset:2048
	ds_read_b128 v[140:143], v169 offset:3072
	ds_read_b128 v[160:163], v170
	ds_read_b128 v[172:175], v170 offset:1024
	ds_read_b128 v[176:179], v170 offset:2048
	ds_read_b128 v[180:183], v170 offset:3072
	s_add_u32 s38, s34, 0xfffc0080
	s_addc_u32 s39, s35, -1
	s_cmp_eq_u32 s65, 12
	s_cselect_b32 s41, s25, s39
	s_cselect_b32 s40, s61, s38
	s_cselect_b32 s39, s21, s64
	s_cselect_b32 s38, s62, s63
	v_lshl_add_u64 v[164:165], s[34:35], 0, v[152:153]
	s_add_i32 m0, s31, 0xc000
	ds_read_b128 v[184:187], v171
	ds_read_b128 v[188:191], v171 offset:1024
	ds_read_b128 v[192:195], v171 offset:2048
	ds_read_b128 v[196:199], v171 offset:3072
	ds_read_b128 v[200:203], v171 offset:4096
	ds_read_b128 v[204:207], v171 offset:5120
	ds_read_b128 v[208:211], v171 offset:6144
	ds_read_b128 v[212:215], v171 offset:7168
	global_load_lds_dwordx4 v[164:165], off
	v_lshl_add_u64 v[164:165], s[34:35], 0, v[154:155]
	s_add_i32 m0, s31, 0xe000
	s_nop 0
	global_load_lds_dwordx4 v[164:165], off
	s_waitcnt vmcnt(8)
	s_waitcnt lgkmcnt(0)
	s_barrier
; #define PG8_STAGE(bufoff, gbase, voff) do { _Pragma("unroll") for (int _i = 0; _i < 2; ++_i) \
;         __builtin_amdgcn_global_load_lds((const unsigned*)((const char*)(gbase) + (voff)[_i]), (PG8_LAS unsigned*)(lds + (bufoff) + ldsw + _i * 8192), 16, 0, 0); } while (0)
; #define PG8_LDA(dst, b, h) do { _Pragma("unroll") for (int m = 0; m < 4; ++m) _Pragma("unroll") for (int k = 0; k < 2; ++k) dst[m][k] = *(const PG8_LAS bf16x8*)(lds + PG8_SA(b, h) + aoff + m * 2048 + k * 1024); } while (0)
; #define PG8_MMA(ai, bj, At, Bt) do { __builtin_amdgcn_s_setprio(1); _Pragma("unroll") for (int m = 0; m < 4; ++m) _Pragma("unroll") for (int n = 0; n < 2; ++n) _Pragma("unroll") for (int k = 0; k < 2; ++k) \
;         acc[ai][bj][m][n] = __builtin_amdgcn_mfma_f32_16x16x32_bf16(Bt[n][k], At[m][k], acc[ai][bj][m][n], 0, 0, 0); __builtin_amdgcn_s_setprio(0); } while (0)
; #define PG8_WAIT_V(n) asm volatile("s_waitcnt vmcnt(" #n ")" ::: "memory")
; #define PG8_WAIT_L(n) asm volatile("s_waitcnt lgkmcnt(" #n ")" ::: "memory")
; #define PG8_BAR __builtin_amdgcn_s_barrier()
; #define PG8_SCHED __builtin_amdgcn_sched_barrier(0)
; template <class Epi, class Sched, bool ALIGN_EPI = false, bool SP2 = false>
; __device__ __forceinline__ void gemm_phase(PG8_LAS unsigned char* lds, const Gemm g, const Sched& S, const Epi& E) {
;     ...
;             PG8_WAIT_V(8); PG8_WAIT_L(0); PG8_BAR; PG8_MMA(0, 0, At, B0); PG8_MMA(0, 1, At, B1); PG8_BAR; PG8_SCHED;
;             PG8_LDA(At, 0, 1); PG8_STAGE(PG8_SB(0, 0), b2, voffB); PG8_STAGE(PG8_SB(0, 1), b2 + hstep, voffB); PG8_STAGE(PG8_SA(0, 0), a2, voffA);
;             PG8_WAIT_V(8); PG8_WAIT_L(0); PG8_BAR; PG8_MMA(1, 0, At, B0); PG8_MMA(1, 1, At, B1); PG8_BAR; PG8_SCHED;
	s_setprio 1
	s_waitcnt lgkmcnt(0)
	v_mfma_f32_16x16x32_bf16 v[124:127], v[128:131], v[184:187], v[124:127]
	v_mfma_f32_16x16x32_bf16 v[120:123], v[136:139], v[184:187], v[120:123]
	v_mfma_f32_16x16x32_bf16 v[116:119], v[128:131], v[192:195], v[116:119]
	v_mfma_f32_16x16x32_bf16 v[112:115], v[136:139], v[192:195], v[112:115]
	v_mfma_f32_16x16x32_bf16 v[96:99], v[128:131], v[200:203], v[96:99]
	v_mfma_f32_16x16x32_bf16 v[88:91], v[136:139], v[200:203], v[88:91]
	v_mfma_f32_16x16x32_bf16 v[84:87], v[128:131], v[208:211], v[84:87]
	v_mfma_f32_16x16x32_bf16 v[76:79], v[136:139], v[208:211], v[76:79]
	v_mfma_f32_16x16x32_bf16 v[124:127], v[132:135], v[188:191], v[124:127]
	v_mfma_f32_16x16x32_bf16 v[120:123], v[140:143], v[188:191], v[120:123]
	v_mfma_f32_16x16x32_bf16 v[116:119], v[132:135], v[196:199], v[116:119]
	v_mfma_f32_16x16x32_bf16 v[112:115], v[140:143], v[196:199], v[112:115]
	v_mfma_f32_16x16x32_bf16 v[96:99], v[132:135], v[204:207], v[96:99]
	v_mfma_f32_16x16x32_bf16 v[88:91], v[140:143], v[204:207], v[88:91]
	v_mfma_f32_16x16x32_bf16 v[84:87], v[132:135], v[212:215], v[84:87]
	v_mfma_f32_16x16x32_bf16 v[76:79], v[140:143], v[212:215], v[76:79]
	s_setprio 0
	s_setprio 1
	v_mfma_f32_16x16x32_bf16 v[108:111], v[160:163], v[184:187], v[108:111]
	v_mfma_f32_16x16x32_bf16 v[104:107], v[176:179], v[184:187], v[104:107]
	v_mfma_f32_16x16x32_bf16 v[100:103], v[160:163], v[192:195], v[100:103]
	v_mfma_f32_16x16x32_bf16 v[92:95], v[176:179], v[192:195], v[92:95]
	v_mfma_f32_16x16x32_bf16 v[80:83], v[160:163], v[200:203], v[80:83]
	v_mfma_f32_16x16x32_bf16 v[72:75], v[176:179], v[200:203], v[72:75]
	v_mfma_f32_16x16x32_bf16 v[68:71], v[160:163], v[208:211], v[68:71]
	v_mfma_f32_16x16x32_bf16 v[64:67], v[176:179], v[208:211], v[64:67]
	v_mfma_f32_16x16x32_bf16 v[108:111], v[172:175], v[188:191], v[108:111]
	v_mfma_f32_16x16x32_bf16 v[104:107], v[180:183], v[188:191], v[104:107]
	v_mfma_f32_16x16x32_bf16 v[100:103], v[172:175], v[196:199], v[100:103]
	v_mfma_f32_16x16x32_bf16 v[92:95], v[180:183], v[196:199], v[92:95]
	v_mfma_f32_16x16x32_bf16 v[80:83], v[172:175], v[204:207], v[80:83]
	v_mfma_f32_16x16x32_bf16 v[72:75], v[180:183], v[204:207], v[72:75]
	v_mfma_f32_16x16x32_bf16 v[68:71], v[172:175], v[212:215], v[68:71]
	v_mfma_f32_16x16x32_bf16 v[64:67], v[180:183], v[212:215], v[64:67]
	s_setprio 0
	s_barrier
	s_add_i32 s68, s58, s45
	v_lshl_add_u64 v[164:165], s[38:39], 0, v[146:147]
	s_mov_b32 m0, s68
	ds_read_b128 v[184:187], v171 offset:16384
	ds_read_b128 v[188:191], v171 offset:17408
	ds_read_b128 v[192:195], v171 offset:18432
	ds_read_b128 v[196:199], v171 offset:19456
	ds_read_b128 v[200:203], v171 offset:20480
	ds_read_b128 v[204:207], v171 offset:21504
	ds_read_b128 v[208:211], v171 offset:22528
	ds_read_b128 v[212:215], v171 offset:23552
	global_load_lds_dwordx4 v[164:165], off
	s_add_i32 m0, s68, 0x2000
	s_add_u32 s68, s38, 0x40000
	v_lshl_add_u64 v[216:217], s[38:39], 0, v[150:151]
	s_addc_u32 s69, s39, 0
	s_add_i32 s70, s59, s45
	global_load_lds_dwordx4 v[216:217], off
	v_lshl_add_u64 v[218:219], s[68:69], 0, v[146:147]
	s_mov_b32 m0, s70
	v_lshl_add_u64 v[220:221], s[40:41], 0, v[148:149]
	global_load_lds_dwordx4 v[218:219], off
	v_lshl_add_u64 v[218:219], s[68:69], 0, v[150:151]
	s_add_i32 m0, s70, 0x2000
	s_nop 0
	global_load_lds_dwordx4 v[218:219], off
	v_lshl_add_u64 v[218:219], s[40:41], 0, v[144:145]
	s_mov_b32 m0, s31
	s_nop 0
	global_load_lds_dwordx4 v[218:219], off
	s_mov_b32 m0, s48
	s_nop 0
	global_load_lds_dwordx4 v[220:221], off
	s_waitcnt vmcnt(8)
	s_waitcnt lgkmcnt(0)
	s_barrier
	s_setprio 1
	s_waitcnt lgkmcnt(0)
	v_mfma_f32_16x16x32_bf16 v[60:63], v[128:131], v[184:187], v[60:63]
	v_mfma_f32_16x16x32_bf16 v[56:59], v[136:139], v[184:187], v[56:59]
	v_mfma_f32_16x16x32_bf16 v[52:55], v[128:131], v[192:195], v[52:55]
	v_mfma_f32_16x16x32_bf16 v[48:51], v[136:139], v[192:195], v[48:51]
	v_mfma_f32_16x16x32_bf16 v[36:39], v[128:131], v[200:203], v[36:39]
	v_mfma_f32_16x16x32_bf16 v[24:27], v[136:139], v[200:203], v[24:27]
	v_mfma_f32_16x16x32_bf16 v[20:23], v[128:131], v[208:211], v[20:23]
	v_mfma_f32_16x16x32_bf16 v[12:15], v[136:139], v[208:211], v[12:15]
	v_mfma_f32_16x16x32_bf16 v[60:63], v[132:135], v[188:191], v[60:63]
	v_mfma_f32_16x16x32_bf16 v[56:59], v[140:143], v[188:191], v[56:59]
	v_mfma_f32_16x16x32_bf16 v[52:55], v[132:135], v[196:199], v[52:55]
	v_mfma_f32_16x16x32_bf16 v[48:51], v[140:143], v[196:199], v[48:51]
	v_mfma_f32_16x16x32_bf16 v[36:39], v[132:135], v[204:207], v[36:39]
	v_mfma_f32_16x16x32_bf16 v[24:27], v[140:143], v[204:207], v[24:27]
	v_mfma_f32_16x16x32_bf16 v[20:23], v[132:135], v[212:215], v[20:23]
	v_mfma_f32_16x16x32_bf16 v[12:15], v[140:143], v[212:215], v[12:15]
	s_setprio 0
	s_setprio 1
	v_mfma_f32_16x16x32_bf16 v[44:47], v[160:163], v[184:187], v[44:47]
	v_mfma_f32_16x16x32_bf16 v[40:43], v[176:179], v[184:187], v[40:43]
	v_mfma_f32_16x16x32_bf16 v[32:35], v[160:163], v[192:195], v[32:35]
	v_mfma_f32_16x16x32_bf16 v[28:31], v[176:179], v[192:195], v[28:31]
	v_mfma_f32_16x16x32_bf16 v[16:19], v[160:163], v[200:203], v[16:19]
	v_mfma_f32_16x16x32_bf16 v[8:11], v[176:179], v[200:203], v[8:11]
	v_mfma_f32_16x16x32_bf16 v[4:7], v[160:163], v[208:211], v[4:7]
	v_mfma_f32_16x16x32_bf16 v[0:3], v[176:179], v[208:211], v[0:3]
	v_mfma_f32_16x16x32_bf16 v[44:47], v[172:175], v[188:191], v[44:47]
	v_mfma_f32_16x16x32_bf16 v[40:43], v[180:183], v[188:191], v[40:43]
	v_mfma_f32_16x16x32_bf16 v[32:35], v[172:175], v[196:199], v[32:35]
	v_mfma_f32_16x16x32_bf16 v[28:31], v[180:183], v[196:199], v[28:31]
	v_mfma_f32_16x16x32_bf16 v[16:19], v[172:175], v[204:207], v[16:19]
	v_mfma_f32_16x16x32_bf16 v[8:11], v[180:183], v[204:207], v[8:11]
	v_mfma_f32_16x16x32_bf16 v[4:7], v[172:175], v[212:215], v[4:7]
	v_mfma_f32_16x16x32_bf16 v[0:3], v[180:183], v[212:215], v[0:3]
	s_setprio 0
	s_barrier
; #define PG8_STAGE(bufoff, gbase, voff) do { _Pragma("unroll") for (int _i = 0; _i < 2; ++_i) \
;         __builtin_amdgcn_global_load_lds((const unsigned*)((const char*)(gbase) + (voff)[_i]), (PG8_LAS unsigned*)(lds + (bufoff) + ldsw + _i * 8192), 16, 0, 0); } while (0)
; #define PG8_LDA(dst, b, h) do { _Pragma("unroll") for (int m = 0; m < 4; ++m) _Pragma("unroll") for (int k = 0; k < 2; ++k) dst[m][k] = *(const PG8_LAS bf16x8*)(lds + PG8_SA(b, h) + aoff + m * 2048 + k * 1024); } while (0)
; #define PG8_LDB(dst, b, h) do { _Pragma("unroll") for (int n = 0; n < 2; ++n) _Pragma("unroll") for (int k = 0; k < 2; ++k) dst[n][k] = *(const PG8_LAS bf16x8*)(lds + PG8_SB(b, h) + boff + n * 2048 + k * 1024); } while (0)
; #define PG8_MMA(ai, bj, At, Bt) do { __builtin_amdgcn_s_setprio(1); _Pragma("unroll") for (int m = 0; m < 4; ++m) _Pragma("unroll") for (int n = 0; n < 2; ++n) _Pragma("unroll") for (int k = 0; k < 2; ++k) \
;         acc[ai][bj][m][n] = __builtin_amdgcn_mfma_f32_16x16x32_bf16(Bt[n][k], At[m][k], acc[ai][bj][m][n], 0, 0, 0); __builtin_amdgcn_s_setprio(0); } while (0)
; #define PG8_WAIT_V(n) asm volatile("s_waitcnt vmcnt(" #n ")" ::: "memory")
; #define PG8_WAIT_L(n) asm volatile("s_waitcnt lgkmcnt(" #n ")" ::: "memory")
; #define PG8_BAR __builtin_amdgcn_s_barrier()
; #define PG8_SCHED __builtin_amdgcn_sched_barrier(0)
; template <class Epi, class Sched, bool ALIGN_EPI = false, bool SP2 = false>
; __device__ __forceinline__ void gemm_phase(PG8_LAS unsigned char* lds, const Gemm g, const Sched& S, const Epi& E) {
;     ...
;             PG8_LDB(B0, 1, 0); PG8_LDB(B1, 1, 1); PG8_SCHED; PG8_LDA(At, 1, 0); PG8_STAGE(PG8_SA(0, 1), a2 + hstep, voffA);
;             PG8_WAIT_V(8); PG8_WAIT_L(0); PG8_BAR; PG8_MMA(0, 0, At, B0); PG8_MMA(0, 1, At, B1); PG8_BAR; PG8_SCHED;
;             PG8_LDA(At, 1, 1); PG8_STAGE(PG8_SB(1, 0), b3, voffB); PG8_STAGE(PG8_SB(1, 1), b3 + hstep, voffB); PG8_STAGE(PG8_SA(1, 0), a3, voffA);
	s_add_i32 s68, 0, 0x18000
	s_add_i32 s69, 0, 0x1c000
	v_add_u32_e32 v140, s68, v167
	v_add_u32_e32 v180, s69, v167
	ds_read_b128 v[128:131], v140
	ds_read_b128 v[132:135], v140 offset:1024
	ds_read_b128 v[136:139], v140 offset:2048
	ds_read_b128 v[140:143], v140 offset:3072
	ds_read_b128 v[160:163], v180
	ds_read_b128 v[172:175], v180 offset:1024
	ds_read_b128 v[176:179], v180 offset:2048
	ds_read_b128 v[180:183], v180 offset:3072
	s_add_u32 s40, s40, 0x40000
	s_addc_u32 s41, s41, 0
	s_mov_b32 m0, s49
	v_lshl_add_u64 v[222:223], s[40:41], 0, v[144:145]
	ds_read_b128 v[184:187], v171 offset:32768
	ds_read_b128 v[188:191], v171 offset:33792
	ds_read_b128 v[192:195], v171 offset:34816
	ds_read_b128 v[196:199], v171 offset:35840
	ds_read_b128 v[200:203], v171 offset:36864
	ds_read_b128 v[204:207], v171 offset:37888
	ds_read_b128 v[208:211], v171 offset:38912
	ds_read_b128 v[212:215], v171 offset:39936
	global_load_lds_dwordx4 v[222:223], off
	v_lshl_add_u64 v[222:223], s[40:41], 0, v[148:149]
	s_mov_b32 m0, s50
	s_nop 0
	global_load_lds_dwordx4 v[222:223], off
	s_waitcnt vmcnt(8)
	s_waitcnt lgkmcnt(0)
	s_barrier
	s_setprio 1
	s_waitcnt lgkmcnt(0)
	v_mfma_f32_16x16x32_bf16 v[124:127], v[128:131], v[184:187], v[124:127]
	v_mfma_f32_16x16x32_bf16 v[120:123], v[136:139], v[184:187], v[120:123]
	v_mfma_f32_16x16x32_bf16 v[116:119], v[128:131], v[192:195], v[116:119]
	v_mfma_f32_16x16x32_bf16 v[112:115], v[136:139], v[192:195], v[112:115]
	v_mfma_f32_16x16x32_bf16 v[96:99], v[128:131], v[200:203], v[96:99]
	v_mfma_f32_16x16x32_bf16 v[88:91], v[136:139], v[200:203], v[88:91]
	v_mfma_f32_16x16x32_bf16 v[84:87], v[128:131], v[208:211], v[84:87]
	v_mfma_f32_16x16x32_bf16 v[76:79], v[136:139], v[208:211], v[76:79]
	v_mfma_f32_16x16x32_bf16 v[124:127], v[132:135], v[188:191], v[124:127]
	v_mfma_f32_16x16x32_bf16 v[120:123], v[140:143], v[188:191], v[120:123]
	v_mfma_f32_16x16x32_bf16 v[116:119], v[132:135], v[196:199], v[116:119]
	v_mfma_f32_16x16x32_bf16 v[112:115], v[140:143], v[196:199], v[112:115]
	v_mfma_f32_16x16x32_bf16 v[96:99], v[132:135], v[204:207], v[96:99]
	v_mfma_f32_16x16x32_bf16 v[88:91], v[140:143], v[204:207], v[88:91]
	v_mfma_f32_16x16x32_bf16 v[84:87], v[132:135], v[212:215], v[84:87]
	v_mfma_f32_16x16x32_bf16 v[76:79], v[140:143], v[212:215], v[76:79]
	s_setprio 0
	s_setprio 1
	v_mfma_f32_16x16x32_bf16 v[108:111], v[160:163], v[184:187], v[108:111]
	v_mfma_f32_16x16x32_bf16 v[104:107], v[176:179], v[184:187], v[104:107]
	v_mfma_f32_16x16x32_bf16 v[100:103], v[160:163], v[192:195], v[100:103]
	v_mfma_f32_16x16x32_bf16 v[92:95], v[176:179], v[192:195], v[92:95]
	v_mfma_f32_16x16x32_bf16 v[80:83], v[160:163], v[200:203], v[80:83]
	v_mfma_f32_16x16x32_bf16 v[72:75], v[176:179], v[200:203], v[72:75]
	v_mfma_f32_16x16x32_bf16 v[68:71], v[160:163], v[208:211], v[68:71]
	v_mfma_f32_16x16x32_bf16 v[64:67], v[176:179], v[208:211], v[64:67]
	v_mfma_f32_16x16x32_bf16 v[108:111], v[172:175], v[188:191], v[108:111]
	v_mfma_f32_16x16x32_bf16 v[104:107], v[180:183], v[188:191], v[104:107]
	v_mfma_f32_16x16x32_bf16 v[100:103], v[172:175], v[196:199], v[100:103]
	v_mfma_f32_16x16x32_bf16 v[92:95], v[180:183], v[196:199], v[92:95]
	v_mfma_f32_16x16x32_bf16 v[80:83], v[172:175], v[204:207], v[80:83]
	v_mfma_f32_16x16x32_bf16 v[72:75], v[180:183], v[204:207], v[72:75]
	v_mfma_f32_16x16x32_bf16 v[68:71], v[172:175], v[212:215], v[68:71]
	v_mfma_f32_16x16x32_bf16 v[64:67], v[180:183], v[212:215], v[64:67]
	s_setprio 0
	s_barrier
	s_add_i32 s40, s68, s45
	v_lshl_add_u64 v[164:165], v[164:165], 0, s[6:7]
	s_mov_b32 m0, s40
	ds_read_b128 v[184:187], v171 offset:49152
	ds_read_b128 v[188:191], v171 offset:50176
	ds_read_b128 v[192:195], v171 offset:51200
	ds_read_b128 v[196:199], v171 offset:52224
	ds_read_b128 v[200:203], v171 offset:53248
	ds_read_b128 v[204:207], v171 offset:54272
	ds_read_b128 v[208:211], v171 offset:55296
	ds_read_b128 v[212:215], v171 offset:56320
	global_load_lds_dwordx4 v[164:165], off
	s_add_i32 m0, s40, 0x2000
	s_add_u32 s38, s38, 0x40080
	v_lshl_add_u64 v[164:165], v[216:217], 0, s[6:7]
	s_addc_u32 s39, s39, 0
	s_add_i32 s40, s69, s45
	global_load_lds_dwordx4 v[164:165], off
	v_lshl_add_u64 v[164:165], s[38:39], 0, v[146:147]
	s_mov_b32 m0, s40
	s_nop 0
	global_load_lds_dwordx4 v[164:165], off
	v_lshl_add_u64 v[164:165], s[38:39], 0, v[150:151]
	s_add_i32 m0, s40, 0x2000
	s_nop 0
	global_load_lds_dwordx4 v[164:165], off
	v_lshl_add_u64 v[164:165], v[218:219], 0, s[6:7]
	s_mov_b32 m0, s56
	s_nop 0
	global_load_lds_dwordx4 v[164:165], off
	v_lshl_add_u64 v[164:165], v[220:221], 0, s[6:7]
	s_mov_b32 m0, s57
	s_nop 0
	global_load_lds_dwordx4 v[164:165], off
	s_waitcnt vmcnt(8)
	s_waitcnt lgkmcnt(0)
	s_barrier
; template <class Epi, class Sched, bool ALIGN_EPI = false, bool SP2 = false>
; __device__ __forceinline__ void gemm_phase(PG8_LAS unsigned char* lds, const Gemm g, const Sched& S, const Epi& E) {
;     ...
;             PG8_WAIT_V(8); PG8_WAIT_L(0); PG8_BAR; PG8_MMA(1, 0, At, B0); PG8_MMA(1, 1, At, B1); PG8_BAR; PG8_SCHED;
;             } else {
;             PG8_LDB(B0, 0, 0); PG8_SCHED; PG8_LDA(At, 0, 0); PG8_STAGE(PG8_SA(1, 1), a1 + hstep, voffA);
;             PG8_WAIT_L(8); PG8_BAR; PG8_WAIT_L(0); PG8_MMA(0, 0, At, B0); PG8_BAR; PG8_SCHED;
;             PG8_LDB(B1, 0, 1); PG8_STAGE(PG8_SB(0, 0), b2, voffB);
;             PG8_BAR; PG8_WAIT_L(0); PG8_MMA(0, 1, At, B1); PG8_BAR;
;             PG8_LDA(At, 0, 1); PG8_STAGE(PG8_SA(0, 0), a2, voffA);
;             PG8_BAR; PG8_WAIT_L(0); PG8_MMA(1, 0, At, B0); PG8_BAR; PG8_SCHED;
;             PG8_STAGE(PG8_SB(0, 1), b2 + hstep, voffB);
;             PG8_WAIT_V(6); PG8_BAR; PG8_MMA(1, 1, At, B1); PG8_BAR;
;             PG8_LDB(B0, 1, 0); PG8_SCHED; PG8_LDA(At, 1, 0); PG8_STAGE(PG8_SA(0, 1), a2 + hstep, voffA);
;             PG8_WAIT_L(8); PG8_BAR; PG8_WAIT_L(0); PG8_MMA(0, 0, At, B0); PG8_BAR; PG8_SCHED;
;             PG8_LDB(B1, 1, 1); PG8_STAGE(PG8_SB(1, 0), b3, voffB);
;             PG8_BAR; PG8_WAIT_L(0); PG8_MMA(0, 1, At, B1); PG8_BAR;
;             PG8_LDA(At, 1, 1); PG8_STAGE(PG8_SA(1, 0), a3, voffA);
;             PG8_BAR; PG8_WAIT_L(0); PG8_MMA(1, 0, At, B0); PG8_BAR; PG8_SCHED;
;             PG8_STAGE(PG8_SB(1, 1), b3 + hstep, voffB);
;             PG8_WAIT_V(6); PG8_BAR; PG8_MMA(1, 1, At, B1); PG8_BAR;
;             }
;         }
;         if constexpr (ALIGN_EPI) { if (wr == 0) PG8_BAR; }
;     __device__ __forceinline__ void operator()(const f32x4 (&acc)[2][2][4][2], const pg8::Unit& u, int wr, int wc, int fr, int fq) const {
;         const int row0 = u.pm * 256 + wr * 64 + fr, col0 = u.pn * 256 + wc * 32 + 8 * fq;
;         const int s = (u.pm * 256 < NP) ? ((u.pm * 256) >> 12) : 16;
;         const float* gate = mod + s * 3072 + 2048;
;         f32x4 gv[2][2];
; #pragma unroll
;         for (int bj = 0; bj < 2; ++bj)
; #pragma unroll
;             for (int n = 0; n < 2; ++n) gv[bj][n] = *(const f32x4*)(gate + col0 + 128 * bj + 4 * n);
;         const float* xbase = (u.pm * 256 < NP) ? xp : xs - (size_t)NP * DM;
;         f32x4 xv[2][2][2][2];
;     ...
;         EO_LOAD(0); EO_FENCE(); EO_LOAD(1); EO_FENCE();
	s_setprio 1
	s_waitcnt lgkmcnt(0)
	v_mfma_f32_16x16x32_bf16 v[60:63], v[128:131], v[184:187], v[60:63]
	v_mfma_f32_16x16x32_bf16 v[56:59], v[136:139], v[184:187], v[56:59]
	v_mfma_f32_16x16x32_bf16 v[52:55], v[128:131], v[192:195], v[52:55]
	v_mfma_f32_16x16x32_bf16 v[48:51], v[136:139], v[192:195], v[48:51]
	v_mfma_f32_16x16x32_bf16 v[36:39], v[128:131], v[200:203], v[36:39]
	v_mfma_f32_16x16x32_bf16 v[24:27], v[136:139], v[200:203], v[24:27]
	v_mfma_f32_16x16x32_bf16 v[20:23], v[128:131], v[208:211], v[20:23]
	v_mfma_f32_16x16x32_bf16 v[12:15], v[136:139], v[208:211], v[12:15]
	v_mfma_f32_16x16x32_bf16 v[60:63], v[132:135], v[188:191], v[60:63]
	v_mfma_f32_16x16x32_bf16 v[56:59], v[140:143], v[188:191], v[56:59]
	v_mfma_f32_16x16x32_bf16 v[52:55], v[132:135], v[196:199], v[52:55]
	v_mfma_f32_16x16x32_bf16 v[48:51], v[140:143], v[196:199], v[48:51]
	v_mfma_f32_16x16x32_bf16 v[36:39], v[132:135], v[204:207], v[36:39]
	v_mfma_f32_16x16x32_bf16 v[24:27], v[140:143], v[204:207], v[24:27]
	v_mfma_f32_16x16x32_bf16 v[20:23], v[132:135], v[212:215], v[20:23]
	v_mfma_f32_16x16x32_bf16 v[12:15], v[140:143], v[212:215], v[12:15]
	s_setprio 0
	s_setprio 1
	v_mfma_f32_16x16x32_bf16 v[44:47], v[160:163], v[184:187], v[44:47]
	v_mfma_f32_16x16x32_bf16 v[40:43], v[176:179], v[184:187], v[40:43]
	v_mfma_f32_16x16x32_bf16 v[32:35], v[160:163], v[192:195], v[32:35]
	v_mfma_f32_16x16x32_bf16 v[28:31], v[176:179], v[192:195], v[28:31]
	v_mfma_f32_16x16x32_bf16 v[16:19], v[160:163], v[200:203], v[16:19]
	v_mfma_f32_16x16x32_bf16 v[8:11], v[176:179], v[200:203], v[8:11]
	v_mfma_f32_16x16x32_bf16 v[4:7], v[160:163], v[208:211], v[4:7]
	v_mfma_f32_16x16x32_bf16 v[0:3], v[176:179], v[208:211], v[0:3]
	v_mfma_f32_16x16x32_bf16 v[44:47], v[172:175], v[188:191], v[44:47]
	v_mfma_f32_16x16x32_bf16 v[40:43], v[180:183], v[188:191], v[40:43]
	v_mfma_f32_16x16x32_bf16 v[32:35], v[172:175], v[196:199], v[32:35]
	v_mfma_f32_16x16x32_bf16 v[28:31], v[180:183], v[196:199], v[28:31]
	v_mfma_f32_16x16x32_bf16 v[16:19], v[172:175], v[204:207], v[16:19]
	v_mfma_f32_16x16x32_bf16 v[8:11], v[180:183], v[204:207], v[8:11]
	v_mfma_f32_16x16x32_bf16 v[4:7], v[172:175], v[212:215], v[4:7]
	v_mfma_f32_16x16x32_bf16 v[0:3], v[180:183], v[212:215], v[0:3]
	s_setprio 0
	s_add_i32 s65, s65, 2
	s_add_u32 s34, s34, 0x100
	s_addc_u32 s35, s35, 0
	s_add_u32 s63, s63, 0x100
	s_addc_u32 s64, s64, 0
	s_cmp_gt_u32 s65, 13
	s_cbranch_scc1 .Lp4_kexit
	s_barrier
	s_branch .LBB0_457
.Lp4_kexit:
	s_and_b64 vcc, exec, s[8:9]
	s_cbranch_vccz .LBB0_460
	s_barrier
.LBB0_460:
	s_add_u32 s68, s61, 0x40080
	s_addc_u32 s69, s25, 0
	v_lshl_add_u64 v[164:165], s[68:69], 0, v[152:153]
	s_add_i32 m0, s31, 0xc000
	v_lshl_add_u64 v[216:217], s[68:69], 0, v[154:155]
	global_load_lds_dwordx4 v[164:165], off
	s_add_i32 m0, s31, 0xe000
	s_nop 0
	global_load_lds_dwordx4 v[216:217], off
	s_lshr_b32 s21, s30, 4
	s_cmpk_lt_i32 s30, 0x100
	s_mulk_i32 s21, 0xc00
	s_cselect_b32 s34, s21, 0xc000
	s_cselect_b32 s38, s36, s54
	s_cselect_b32 s39, s37, s55
	s_ashr_i32 s35, s34, 31
	v_lshl_or_b32 v128, s60, 8, v168
	s_lshl_b64 s[34:35], s[34:35], 2
	s_add_u32 s34, s22, s34
	v_ashrrev_i32_e32 v129, 31, v128
	v_lshl_add_u32 v220, s30, 8, v166
	s_addc_u32 s35, s23, s35
	v_lshlrev_b64 v[160:161], 2, v[128:129]
	v_or_b32_e32 v188, 16, v220
	v_lshl_add_u64 v[128:129], s[34:35], 0, v[160:161]
	v_ashrrev_i32_e32 v221, 31, v220
	v_ashrrev_i32_e32 v189, 31, v188
	v_or_b32_e32 v204, 32, v220
	v_lshl_add_u64 v[132:133], v[128:129], 0, s[10:11]
	v_add_co_u32_e32 v128, vcc, s52, v128
	v_lshl_add_u64 v[162:163], s[38:39], 0, v[160:161]
	v_lshlrev_b64 v[164:165], 12, v[220:221]
	v_lshlrev_b64 v[236:237], 12, v[188:189]
	v_ashrrev_i32_e32 v205, 31, v204
	v_addc_co_u32_e32 v129, vcc, 0, v129, vcc
	v_lshl_add_u64 v[184:185], v[162:163], 0, v[164:165]
	v_lshl_add_u64 v[200:201], v[162:163], 0, v[236:237]
	v_lshlrev_b64 v[238:239], 12, v[204:205]
	global_load_dwordx4 v[136:139], v[128:129], off
	s_nop 0
	global_load_dwordx4 v[128:131], v[132:133], off offset:528
	global_load_dwordx4 v[172:175], v[184:185], off offset:16
	global_load_dwordx4 v[176:179], v[184:185], off
	global_load_dwordx4 v[140:143], v[132:133], off offset:16
	s_nop 0
	global_load_dwordx4 v[132:135], v[132:133], off offset:512
	s_nop 0
	global_load_dwordx4 v[180:183], v[184:185], off offset:528
	s_nop 0
	global_load_dwordx4 v[184:187], v[184:185], off offset:512
	s_nop 0
	global_load_dwordx4 v[188:191], v[200:201], off
	global_load_dwordx4 v[192:195], v[200:201], off offset:16
	global_load_dwordx4 v[196:199], v[200:201], off offset:512
	s_nop 0
	global_load_dwordx4 v[200:203], v[200:201], off offset:528
	v_lshl_add_u64 v[216:217], v[162:163], 0, v[238:239]
	v_or_b32_e32 v220, 48, v220
	global_load_dwordx4 v[204:207], v[216:217], off
	global_load_dwordx4 v[208:211], v[216:217], off offset:16
	global_load_dwordx4 v[212:215], v[216:217], off offset:512
	s_nop 0
	global_load_dwordx4 v[216:219], v[216:217], off offset:528
	v_ashrrev_i32_e32 v221, 31, v220
	v_lshlrev_b64 v[240:241], 12, v[220:221]
	v_lshl_add_u64 v[232:233], v[162:163], 0, v[240:241]
	global_load_dwordx4 v[220:223], v[232:233], off
	global_load_dwordx4 v[224:227], v[232:233], off offset:16
	global_load_dwordx4 v[228:231], v[232:233], off offset:512
	s_nop 0
	global_load_dwordx4 v[232:235], v[232:233], off offset:528
	v_lshl_add_u64 v[242:243], s[66:67], 0, v[164:165]
	v_lshl_add_u64 v[242:243], v[242:243], 0, v[160:161]
	v_lshl_add_u64 v[236:237], s[66:67], 0, v[236:237]
	v_lshl_add_u64 v[244:245], v[164:165], 0, s[12:13]
	v_lshl_add_u64 v[236:237], v[236:237], 0, v[160:161]
	v_lshl_add_u64 v[246:247], v[162:163], 0, v[244:245]
	s_andn2_b64 vcc, exec, s[0:1]
	s_mov_b64 s[0:1], -1
	s_waitcnt vmcnt(0)
; #define EO_LOAD(bt_) do { _Pragma("unroll") for (int mm = 0; mm < 2; ++mm) { const float* xr = xbase + (size_t)(row0 + ((bt_) >> 1) * 128 + (2 * ((bt_) & 1) + mm) * 16) * DM + col0; \
;             _Pragma("unroll") for (int bj = 0; bj < 2; ++bj) _Pragma("unroll") for (int n = 0; n < 2; ++n) xv[(bt_) & 1][mm][bj][n] = *(const f32x4*)(xr + 128 * bj + 4 * n); } } while (0)
; #define EO_FENCE() asm volatile("" ::: "memory")
;     __device__ __forceinline__ void operator()(const f32x4 (&acc)[2][2][4][2], const pg8::Unit& u, int wr, int wc, int fr, int fq) const {
;     ...
;         EO_LOAD(0); EO_FENCE(); EO_LOAD(1); EO_FENCE();
;         EO_STORE(0); EO_FENCE(); EO_LOAD(2); EO_FENCE();
;         EO_STORE(1); EO_FENCE(); EO_LOAD(3); EO_FENCE();
;         EO_STORE(2); EO_FENCE(); EO_STORE(3);
	v_pk_fma_f32 v[122:123], v[122:123], v[142:143], v[174:175]
	v_pk_fma_f32 v[126:127], v[126:127], v[138:139], v[178:179]
	v_pk_fma_f32 v[124:125], v[124:125], v[136:137], v[176:177]
	v_pk_fma_f32 v[120:121], v[120:121], v[140:141], v[172:173]
	v_pk_fma_f32 v[110:111], v[110:111], v[134:135], v[186:187]
	v_pk_fma_f32 v[108:109], v[108:109], v[132:133], v[184:185]
	v_pk_fma_f32 v[106:107], v[106:107], v[130:131], v[182:183]
	v_pk_fma_f32 v[104:105], v[104:105], v[128:129], v[180:181]
	v_pk_fma_f32 v[118:119], v[118:119], v[138:139], v[190:191]
	v_pk_fma_f32 v[116:117], v[116:117], v[136:137], v[188:189]
	v_pk_fma_f32 v[114:115], v[114:115], v[142:143], v[194:195]
	v_pk_fma_f32 v[112:113], v[112:113], v[140:141], v[192:193]
	v_pk_fma_f32 v[102:103], v[102:103], v[134:135], v[198:199]
	v_pk_fma_f32 v[100:101], v[100:101], v[132:133], v[196:197]
	v_pk_fma_f32 v[94:95], v[94:95], v[130:131], v[202:203]
	v_pk_fma_f32 v[92:93], v[92:93], v[128:129], v[200:201]
	global_store_dwordx4 v[242:243], v[124:127], off
	global_store_dwordx4 v[242:243], v[120:123], off offset:16
	global_store_dwordx4 v[242:243], v[108:111], off offset:512
	global_store_dwordx4 v[242:243], v[104:107], off offset:528
	global_store_dwordx4 v[236:237], v[116:119], off
	global_store_dwordx4 v[236:237], v[112:115], off offset:16
	global_store_dwordx4 v[236:237], v[100:103], off offset:512
	global_store_dwordx4 v[236:237], v[92:95], off offset:528
	v_lshl_add_u64 v[172:173], v[164:165], 0, s[14:15]
	v_lshl_add_u64 v[174:175], s[66:67], 0, v[238:239]
	v_lshl_add_u64 v[124:125], v[162:163], 0, v[172:173]
	v_lshl_add_u64 v[174:175], v[174:175], 0, v[160:161]
	v_pk_fma_f32 v[74:75], v[74:75], v[130:131], v[218:219]
	v_pk_fma_f32 v[72:73], v[72:73], v[128:129], v[216:217]
	global_load_dwordx4 v[92:95], v[246:247], off offset:16
	global_load_dwordx4 v[100:103], v[246:247], off
	global_load_dwordx4 v[104:107], v[246:247], off offset:528
	global_load_dwordx4 v[108:111], v[246:247], off offset:512
	global_load_dwordx4 v[112:115], v[124:125], off offset:16
	global_load_dwordx4 v[116:119], v[124:125], off
	global_load_dwordx4 v[120:123], v[124:125], off offset:528
	s_nop 0
	global_load_dwordx4 v[124:127], v[124:125], off offset:512
	v_pk_fma_f32 v[82:83], v[82:83], v[134:135], v[214:215]
	v_pk_fma_f32 v[80:81], v[80:81], v[132:133], v[212:213]
	global_store_dwordx4 v[174:175], v[72:75], off offset:528
	global_store_dwordx4 v[174:175], v[80:83], off offset:512
	v_pk_fma_f32 v[98:99], v[98:99], v[138:139], v[206:207]
	v_lshl_add_u64 v[72:73], s[66:67], 0, v[240:241]
	v_lshl_add_u64 v[80:81], v[72:73], 0, v[160:161]
	v_pk_fma_f32 v[74:75], v[86:87], v[138:139], v[222:223]
	v_pk_fma_f32 v[72:73], v[84:85], v[136:137], v[220:221]
	v_pk_fma_f32 v[96:97], v[96:97], v[136:137], v[204:205]
	v_pk_fma_f32 v[90:91], v[90:91], v[142:143], v[210:211]
	v_pk_fma_f32 v[88:89], v[88:89], v[140:141], v[208:209]
	global_store_dwordx4 v[80:81], v[72:75], off
	v_pk_fma_f32 v[70:71], v[70:71], v[134:135], v[230:231]
	v_pk_fma_f32 v[68:69], v[68:69], v[132:133], v[228:229]
	v_pk_fma_f32 v[74:75], v[78:79], v[142:143], v[226:227]
	v_pk_fma_f32 v[72:73], v[76:77], v[140:141], v[224:225]
	v_pk_fma_f32 v[66:67], v[66:67], v[130:131], v[234:235]
	v_pk_fma_f32 v[64:65], v[64:65], v[128:129], v[232:233]
	global_store_dwordx4 v[174:175], v[96:99], off
	global_store_dwordx4 v[174:175], v[88:91], off offset:16
	global_store_dwordx4 v[80:81], v[72:75], off offset:16
	global_store_dwordx4 v[80:81], v[68:71], off offset:512
	global_store_dwordx4 v[80:81], v[64:67], off offset:528
	v_lshl_add_u64 v[174:175], v[164:165], 0, s[16:17]
	v_lshl_add_u64 v[76:77], v[162:163], 0, v[174:175]
	global_load_dwordx4 v[64:67], v[76:77], off
	global_load_dwordx4 v[68:71], v[76:77], off offset:16
	global_load_dwordx4 v[72:75], v[76:77], off offset:512
	s_nop 0
	global_load_dwordx4 v[76:79], v[76:77], off offset:528
	v_lshl_add_u64 v[164:165], v[164:165], 0, s[18:19]
	v_lshl_add_u64 v[96:97], v[162:163], 0, v[164:165]
	global_load_dwordx4 v[80:83], v[96:97], off
	global_load_dwordx4 v[84:87], v[96:97], off offset:16
	global_load_dwordx4 v[88:91], v[96:97], off offset:512
	s_nop 0
	global_load_dwordx4 v[96:99], v[96:97], off offset:528
	v_lshl_add_u64 v[162:163], s[66:67], 0, v[244:245]
	v_lshl_add_u64 v[172:173], s[66:67], 0, v[172:173]
	v_lshl_add_u64 v[174:175], s[66:67], 0, v[174:175]
	v_lshl_add_u64 v[162:163], v[162:163], 0, v[160:161]
	v_lshl_add_u64 v[172:173], v[172:173], 0, v[160:161]
	v_lshl_add_u64 v[174:175], v[174:175], 0, v[160:161]
	s_waitcnt vmcnt(23)
	v_pk_fma_f32 v[58:59], v[58:59], v[142:143], v[94:95]
	s_waitcnt vmcnt(22)
	v_pk_fma_f32 v[62:63], v[62:63], v[138:139], v[102:103]
	v_pk_fma_f32 v[60:61], v[60:61], v[136:137], v[100:101]
	v_pk_fma_f32 v[56:57], v[56:57], v[140:141], v[92:93]
	s_waitcnt vmcnt(20)
	v_pk_fma_f32 v[46:47], v[46:47], v[134:135], v[110:111]
	v_pk_fma_f32 v[44:45], v[44:45], v[132:133], v[108:109]
	v_pk_fma_f32 v[42:43], v[42:43], v[130:131], v[106:107]
	v_pk_fma_f32 v[40:41], v[40:41], v[128:129], v[104:105]
	s_waitcnt vmcnt(18)
	v_pk_fma_f32 v[54:55], v[54:55], v[138:139], v[118:119]
	v_pk_fma_f32 v[52:53], v[52:53], v[136:137], v[116:117]
	v_pk_fma_f32 v[50:51], v[50:51], v[142:143], v[114:115]
	v_pk_fma_f32 v[48:49], v[48:49], v[140:141], v[112:113]
	s_waitcnt vmcnt(16)
; #define PG8_STAGE(bufoff, gbase, voff) do { _Pragma("unroll") for (int _i = 0; _i < 2; ++_i) \
;         __builtin_amdgcn_global_load_lds((const unsigned*)((const char*)(gbase) + (voff)[_i]), (PG8_LAS unsigned*)(lds + (bufoff) + ldsw + _i * 8192), 16, 0, 0); } while (0)
; #define PG8_LDA(dst, b, h) do { _Pragma("unroll") for (int m = 0; m < 4; ++m) _Pragma("unroll") for (int k = 0; k < 2; ++k) dst[m][k] = *(const PG8_LAS bf16x8*)(lds + PG8_SA(b, h) + aoff + m * 2048 + k * 1024); } while (0)
; #define PG8_LDB(dst, b, h) do { _Pragma("unroll") for (int n = 0; n < 2; ++n) _Pragma("unroll") for (int k = 0; k < 2; ++k) dst[n][k] = *(const PG8_LAS bf16x8*)(lds + PG8_SB(b, h) + boff + n * 2048 + k * 1024); } while (0)
; #define PG8_MMA(ai, bj, At, Bt) do { __builtin_amdgcn_s_setprio(1); _Pragma("unroll") for (int m = 0; m < 4; ++m) _Pragma("unroll") for (int n = 0; n < 2; ++n) _Pragma("unroll") for (int k = 0; k < 2; ++k) \
;         acc[ai][bj][m][n] = __builtin_amdgcn_mfma_f32_16x16x32_bf16(Bt[n][k], At[m][k], acc[ai][bj][m][n], 0, 0, 0); __builtin_amdgcn_s_setprio(0); } while (0)
; #define PG8_WAIT_V(n) asm volatile("s_waitcnt vmcnt(" #n ")" ::: "memory")
; #define PG8_WAIT_L(n) asm volatile("s_waitcnt lgkmcnt(" #n ")" ::: "memory")
; #define PG8_BAR __builtin_amdgcn_s_barrier()
; #define PG8_SCHED __builtin_amdgcn_sched_barrier(0)
; #define EO_FENCE() asm volatile("" ::: "memory")
; template <class Epi, class Sched, bool ALIGN_EPI = false, bool SP2 = false>
; __device__ __forceinline__ void gemm_phase(PG8_LAS unsigned char* lds, const Gemm g, const Sched& S, const Epi& E) {
;     ...
;             PG8_LDB(B0, 0, 0); PG8_LDB(B1, 0, 1); PG8_SCHED; PG8_LDA(At, 0, 0); PG8_STAGE(PG8_SA(1, 1), a1 + hstep, voffA);
;             PG8_WAIT_V(8); PG8_WAIT_L(0); PG8_BAR; PG8_MMA(0, 0, At, B0); PG8_MMA(0, 1, At, B1); PG8_BAR; PG8_SCHED;
;     __device__ __forceinline__ void operator()(const f32x4 (&acc)[2][2][4][2], const pg8::Unit& u, int wr, int wc, int fr, int fq) const {
;     ...
;         EO_LOAD(0); EO_FENCE(); EO_LOAD(1); EO_FENCE();
;         EO_STORE(0); EO_FENCE(); EO_LOAD(2); EO_FENCE();
;         EO_STORE(1); EO_FENCE(); EO_LOAD(3); EO_FENCE();
;         EO_STORE(2); EO_FENCE(); EO_STORE(3);
	v_pk_fma_f32 v[34:35], v[34:35], v[134:135], v[126:127]
	v_pk_fma_f32 v[32:33], v[32:33], v[132:133], v[124:125]
	v_pk_fma_f32 v[30:31], v[30:31], v[130:131], v[122:123]
	v_pk_fma_f32 v[28:29], v[28:29], v[128:129], v[120:121]
	global_store_dwordx4 v[162:163], v[60:63], off
	global_store_dwordx4 v[162:163], v[56:59], off offset:16
	global_store_dwordx4 v[162:163], v[44:47], off offset:512
	global_store_dwordx4 v[162:163], v[40:43], off offset:528
	global_store_dwordx4 v[172:173], v[52:55], off
	global_store_dwordx4 v[172:173], v[48:51], off offset:16
	global_store_dwordx4 v[172:173], v[32:35], off offset:512
	global_store_dwordx4 v[172:173], v[28:31], off offset:528
	s_waitcnt vmcnt(14)
	v_pk_fma_f32 v[26:27], v[26:27], v[142:143], v[70:71]
	s_waitcnt vmcnt(13)
	v_pk_fma_f32 v[18:19], v[18:19], v[134:135], v[74:75]
	s_waitcnt vmcnt(12)
	v_pk_fma_f32 v[10:11], v[10:11], v[130:131], v[78:79]
	v_pk_fma_f32 v[8:9], v[8:9], v[128:129], v[76:77]
	v_pk_fma_f32 v[16:17], v[16:17], v[132:133], v[72:73]
	global_store_dwordx4 v[174:175], v[8:11], off offset:528
	global_store_dwordx4 v[174:175], v[16:19], off offset:512
	v_pk_fma_f32 v[30:31], v[38:39], v[138:139], v[66:67]
	v_lshl_add_u64 v[8:9], s[66:67], 0, v[164:165]
	v_lshl_add_u64 v[16:17], v[8:9], 0, v[160:161]
	s_waitcnt vmcnt(13)
	v_pk_fma_f32 v[10:11], v[22:23], v[138:139], v[82:83]
	v_pk_fma_f32 v[8:9], v[20:21], v[136:137], v[80:81]
	v_pk_fma_f32 v[28:29], v[36:37], v[136:137], v[64:65]
	v_pk_fma_f32 v[24:25], v[24:25], v[140:141], v[68:69]
	global_store_dwordx4 v[16:17], v[8:11], off
	s_waitcnt vmcnt(12)
	v_pk_fma_f32 v[6:7], v[6:7], v[134:135], v[90:91]
	v_pk_fma_f32 v[4:5], v[4:5], v[132:133], v[88:89]
	v_pk_fma_f32 v[10:11], v[14:15], v[142:143], v[86:87]
	v_pk_fma_f32 v[8:9], v[12:13], v[140:141], v[84:85]
	s_waitcnt vmcnt(11)
	v_pk_fma_f32 v[2:3], v[2:3], v[130:131], v[98:99]
	v_pk_fma_f32 v[0:1], v[0:1], v[128:129], v[96:97]
	global_store_dwordx4 v[174:175], v[28:31], off
	global_store_dwordx4 v[174:175], v[24:27], off offset:16
	global_store_dwordx4 v[16:17], v[8:11], off offset:16
	global_store_dwordx4 v[16:17], v[4:7], off offset:512
	global_store_dwordx4 v[16:17], v[0:3], off offset:528
	s_cbranch_vccnz .LBB0_453
	s_andn2_b64 vcc, exec, s[4:5]
	s_cbranch_vccnz .LBB0_452
	s_barrier
	s_branch .LBB0_452
.Lp4_peel:
	ds_read_b128 v[128:131], v169
	ds_read_b128 v[132:135], v169 offset:1024
	ds_read_b128 v[136:139], v169 offset:2048
	ds_read_b128 v[140:143], v169 offset:3072
	ds_read_b128 v[160:163], v170
	ds_read_b128 v[172:175], v170 offset:1024
	ds_read_b128 v[176:179], v170 offset:2048
	ds_read_b128 v[180:183], v170 offset:3072
	s_add_u32 s38, s34, 0xfffc0080
	s_addc_u32 s39, s35, -1
	s_cmp_eq_u32 s65, 12
	s_cselect_b32 s41, s25, s39
	s_cselect_b32 s40, s61, s38
	s_cselect_b32 s39, s21, s64
	s_cselect_b32 s38, s62, s63
	ds_read_b128 v[184:187], v171
	ds_read_b128 v[188:191], v171 offset:1024
	ds_read_b128 v[192:195], v171 offset:2048
	ds_read_b128 v[196:199], v171 offset:3072
	ds_read_b128 v[200:203], v171 offset:4096
	ds_read_b128 v[204:207], v171 offset:5120
	ds_read_b128 v[208:211], v171 offset:6144
	ds_read_b128 v[212:215], v171 offset:7168
	s_waitcnt vmcnt(24)
	s_waitcnt lgkmcnt(0)
	s_barrier
	s_setprio 1
	s_waitcnt lgkmcnt(0)
	v_mfma_f32_16x16x32_bf16 v[124:127], v[128:131], v[184:187], 0
	v_mfma_f32_16x16x32_bf16 v[120:123], v[136:139], v[184:187], 0
	v_mfma_f32_16x16x32_bf16 v[116:119], v[128:131], v[192:195], 0
	v_mfma_f32_16x16x32_bf16 v[112:115], v[136:139], v[192:195], 0
	v_mfma_f32_16x16x32_bf16 v[96:99], v[128:131], v[200:203], 0
	v_mfma_f32_16x16x32_bf16 v[88:91], v[136:139], v[200:203], 0
	v_mfma_f32_16x16x32_bf16 v[84:87], v[128:131], v[208:211], 0
	v_mfma_f32_16x16x32_bf16 v[76:79], v[136:139], v[208:211], 0
	v_mfma_f32_16x16x32_bf16 v[124:127], v[132:135], v[188:191], v[124:127]
	v_mfma_f32_16x16x32_bf16 v[120:123], v[140:143], v[188:191], v[120:123]
	v_mfma_f32_16x16x32_bf16 v[116:119], v[132:135], v[196:199], v[116:119]
	v_mfma_f32_16x16x32_bf16 v[112:115], v[140:143], v[196:199], v[112:115]
	v_mfma_f32_16x16x32_bf16 v[96:99], v[132:135], v[204:207], v[96:99]
	v_mfma_f32_16x16x32_bf16 v[88:91], v[140:143], v[204:207], v[88:91]
	v_mfma_f32_16x16x32_bf16 v[84:87], v[132:135], v[212:215], v[84:87]
	v_mfma_f32_16x16x32_bf16 v[76:79], v[140:143], v[212:215], v[76:79]
	s_setprio 0
	s_setprio 1
	v_mfma_f32_16x16x32_bf16 v[108:111], v[160:163], v[184:187], 0
	v_mfma_f32_16x16x32_bf16 v[104:107], v[176:179], v[184:187], 0
	v_mfma_f32_16x16x32_bf16 v[100:103], v[160:163], v[192:195], 0
	v_mfma_f32_16x16x32_bf16 v[92:95], v[176:179], v[192:195], 0
	v_mfma_f32_16x16x32_bf16 v[80:83], v[160:163], v[200:203], 0
	v_mfma_f32_16x16x32_bf16 v[72:75], v[176:179], v[200:203], 0
	v_mfma_f32_16x16x32_bf16 v[68:71], v[160:163], v[208:211], 0
	v_mfma_f32_16x16x32_bf16 v[64:67], v[176:179], v[208:211], 0
	v_mfma_f32_16x16x32_bf16 v[108:111], v[172:175], v[188:191], v[108:111]
	v_mfma_f32_16x16x32_bf16 v[104:107], v[180:183], v[188:191], v[104:107]
	v_mfma_f32_16x16x32_bf16 v[100:103], v[172:175], v[196:199], v[100:103]
	v_mfma_f32_16x16x32_bf16 v[92:95], v[180:183], v[196:199], v[92:95]
	v_mfma_f32_16x16x32_bf16 v[80:83], v[172:175], v[204:207], v[80:83]
	v_mfma_f32_16x16x32_bf16 v[72:75], v[180:183], v[204:207], v[72:75]
	v_mfma_f32_16x16x32_bf16 v[68:71], v[172:175], v[212:215], v[68:71]
	v_mfma_f32_16x16x32_bf16 v[64:67], v[180:183], v[212:215], v[64:67]
	s_setprio 0
	s_barrier
; #define PG8_STAGE(bufoff, gbase, voff) do { _Pragma("unroll") for (int _i = 0; _i < 2; ++_i) \
;         __builtin_amdgcn_global_load_lds((const unsigned*)((const char*)(gbase) + (voff)[_i]), (PG8_LAS unsigned*)(lds + (bufoff) + ldsw + _i * 8192), 16, 0, 0); } while (0)
; #define PG8_LDA(dst, b, h) do { _Pragma("unroll") for (int m = 0; m < 4; ++m) _Pragma("unroll") for (int k = 0; k < 2; ++k) dst[m][k] = *(const PG8_LAS bf16x8*)(lds + PG8_SA(b, h) + aoff + m * 2048 + k * 1024); } while (0)
; #define PG8_LDB(dst, b, h) do { _Pragma("unroll") for (int n = 0; n < 2; ++n) _Pragma("unroll") for (int k = 0; k < 2; ++k) dst[n][k] = *(const PG8_LAS bf16x8*)(lds + PG8_SB(b, h) + boff + n * 2048 + k * 1024); } while (0)
; #define PG8_MMA(ai, bj, At, Bt) do { __builtin_amdgcn_s_setprio(1); _Pragma("unroll") for (int m = 0; m < 4; ++m) _Pragma("unroll") for (int n = 0; n < 2; ++n) _Pragma("unroll") for (int k = 0; k < 2; ++k) \
;         acc[ai][bj][m][n] = __builtin_amdgcn_mfma_f32_16x16x32_bf16(Bt[n][k], At[m][k], acc[ai][bj][m][n], 0, 0, 0); __builtin_amdgcn_s_setprio(0); } while (0)
; #define PG8_WAIT_V(n) asm volatile("s_waitcnt vmcnt(" #n ")" ::: "memory")
; #define PG8_WAIT_L(n) asm volatile("s_waitcnt lgkmcnt(" #n ")" ::: "memory")
; #define PG8_BAR __builtin_amdgcn_s_barrier()
; #define PG8_SCHED __builtin_amdgcn_sched_barrier(0)
; template <class Epi, class Sched, bool ALIGN_EPI = false, bool SP2 = false>
; __device__ __forceinline__ void gemm_phase(PG8_LAS unsigned char* lds, const Gemm g, const Sched& S, const Epi& E) {
;     ...
;             PG8_LDA(At, 0, 1); PG8_STAGE(PG8_SB(0, 0), b2, voffB); PG8_STAGE(PG8_SB(0, 1), b2 + hstep, voffB); PG8_STAGE(PG8_SA(0, 0), a2, voffA);
;             PG8_WAIT_V(8); PG8_WAIT_L(0); PG8_BAR; PG8_MMA(1, 0, At, B0); PG8_MMA(1, 1, At, B1); PG8_BAR; PG8_SCHED;
;             PG8_LDB(B0, 1, 0); PG8_LDB(B1, 1, 1); PG8_SCHED; PG8_LDA(At, 1, 0); PG8_STAGE(PG8_SA(0, 1), a2 + hstep, voffA);
	s_add_i32 s68, s58, s45
	v_lshl_add_u64 v[164:165], s[38:39], 0, v[146:147]
	s_mov_b32 m0, s68
	ds_read_b128 v[184:187], v171 offset:16384
	ds_read_b128 v[188:191], v171 offset:17408
	ds_read_b128 v[192:195], v171 offset:18432
	ds_read_b128 v[196:199], v171 offset:19456
	ds_read_b128 v[200:203], v171 offset:20480
	ds_read_b128 v[204:207], v171 offset:21504
	ds_read_b128 v[208:211], v171 offset:22528
	ds_read_b128 v[212:215], v171 offset:23552
	global_load_lds_dwordx4 v[164:165], off
	s_add_i32 m0, s68, 0x2000
	s_add_u32 s68, s38, 0x40000
	v_lshl_add_u64 v[216:217], s[38:39], 0, v[150:151]
	s_addc_u32 s69, s39, 0
	s_add_i32 s70, s59, s45
	global_load_lds_dwordx4 v[216:217], off
	v_lshl_add_u64 v[218:219], s[68:69], 0, v[146:147]
	s_mov_b32 m0, s70
	v_lshl_add_u64 v[220:221], s[40:41], 0, v[148:149]
	global_load_lds_dwordx4 v[218:219], off
	v_lshl_add_u64 v[218:219], s[68:69], 0, v[150:151]
	s_add_i32 m0, s70, 0x2000
	s_nop 0
	global_load_lds_dwordx4 v[218:219], off
	v_lshl_add_u64 v[218:219], s[40:41], 0, v[144:145]
	s_mov_b32 m0, s31
	s_nop 0
	global_load_lds_dwordx4 v[218:219], off
	s_mov_b32 m0, s48
	s_nop 0
	global_load_lds_dwordx4 v[220:221], off
	s_waitcnt vmcnt(24)
	s_waitcnt lgkmcnt(0)
	s_barrier
	s_setprio 1
	s_waitcnt lgkmcnt(0)
	v_mfma_f32_16x16x32_bf16 v[60:63], v[128:131], v[184:187], 0
	v_mfma_f32_16x16x32_bf16 v[56:59], v[136:139], v[184:187], 0
	v_mfma_f32_16x16x32_bf16 v[52:55], v[128:131], v[192:195], 0
	v_mfma_f32_16x16x32_bf16 v[48:51], v[136:139], v[192:195], 0
	v_mfma_f32_16x16x32_bf16 v[36:39], v[128:131], v[200:203], 0
	v_mfma_f32_16x16x32_bf16 v[24:27], v[136:139], v[200:203], 0
	v_mfma_f32_16x16x32_bf16 v[20:23], v[128:131], v[208:211], 0
	v_mfma_f32_16x16x32_bf16 v[12:15], v[136:139], v[208:211], 0
	v_mfma_f32_16x16x32_bf16 v[60:63], v[132:135], v[188:191], v[60:63]
	v_mfma_f32_16x16x32_bf16 v[56:59], v[140:143], v[188:191], v[56:59]
	v_mfma_f32_16x16x32_bf16 v[52:55], v[132:135], v[196:199], v[52:55]
	v_mfma_f32_16x16x32_bf16 v[48:51], v[140:143], v[196:199], v[48:51]
	v_mfma_f32_16x16x32_bf16 v[36:39], v[132:135], v[204:207], v[36:39]
	v_mfma_f32_16x16x32_bf16 v[24:27], v[140:143], v[204:207], v[24:27]
	v_mfma_f32_16x16x32_bf16 v[20:23], v[132:135], v[212:215], v[20:23]
	v_mfma_f32_16x16x32_bf16 v[12:15], v[140:143], v[212:215], v[12:15]
	s_setprio 0
	s_setprio 1
	v_mfma_f32_16x16x32_bf16 v[44:47], v[160:163], v[184:187], 0
	v_mfma_f32_16x16x32_bf16 v[40:43], v[176:179], v[184:187], 0
	v_mfma_f32_16x16x32_bf16 v[32:35], v[160:163], v[192:195], 0
	v_mfma_f32_16x16x32_bf16 v[28:31], v[176:179], v[192:195], 0
	v_mfma_f32_16x16x32_bf16 v[16:19], v[160:163], v[200:203], 0
	v_mfma_f32_16x16x32_bf16 v[8:11], v[176:179], v[200:203], 0
	v_mfma_f32_16x16x32_bf16 v[4:7], v[160:163], v[208:211], 0
	v_mfma_f32_16x16x32_bf16 v[0:3], v[176:179], v[208:211], 0
	v_mfma_f32_16x16x32_bf16 v[44:47], v[172:175], v[188:191], v[44:47]
	v_mfma_f32_16x16x32_bf16 v[40:43], v[180:183], v[188:191], v[40:43]
	v_mfma_f32_16x16x32_bf16 v[32:35], v[172:175], v[196:199], v[32:35]
	v_mfma_f32_16x16x32_bf16 v[28:31], v[180:183], v[196:199], v[28:31]
	v_mfma_f32_16x16x32_bf16 v[16:19], v[172:175], v[204:207], v[16:19]
	v_mfma_f32_16x16x32_bf16 v[8:11], v[180:183], v[204:207], v[8:11]
	v_mfma_f32_16x16x32_bf16 v[4:7], v[172:175], v[212:215], v[4:7]
	v_mfma_f32_16x16x32_bf16 v[0:3], v[180:183], v[212:215], v[0:3]
	s_setprio 0
	s_barrier
	s_add_i32 s68, 0, 0x18000
	s_add_i32 s69, 0, 0x1c000
	v_add_u32_e32 v140, s68, v167
	v_add_u32_e32 v180, s69, v167
	ds_read_b128 v[128:131], v140
	ds_read_b128 v[132:135], v140 offset:1024
	ds_read_b128 v[136:139], v140 offset:2048
	ds_read_b128 v[140:143], v140 offset:3072
	ds_read_b128 v[160:163], v180
	ds_read_b128 v[172:175], v180 offset:1024
	ds_read_b128 v[176:179], v180 offset:2048
	ds_read_b128 v[180:183], v180 offset:3072
	s_add_u32 s40, s40, 0x40000
	s_addc_u32 s41, s41, 0
	s_mov_b32 m0, s49
	v_lshl_add_u64 v[222:223], s[40:41], 0, v[144:145]
	ds_read_b128 v[184:187], v171 offset:32768
	ds_read_b128 v[188:191], v171 offset:33792
	ds_read_b128 v[192:195], v171 offset:34816
	ds_read_b128 v[196:199], v171 offset:35840
	ds_read_b128 v[200:203], v171 offset:36864
	ds_read_b128 v[204:207], v171 offset:37888
	ds_read_b128 v[208:211], v171 offset:38912
	ds_read_b128 v[212:215], v171 offset:39936
	global_load_lds_dwordx4 v[222:223], off
	v_lshl_add_u64 v[222:223], s[40:41], 0, v[148:149]
	s_mov_b32 m0, s50
	s_nop 0
	global_load_lds_dwordx4 v[222:223], off
	s_waitcnt vmcnt(24)
	s_waitcnt lgkmcnt(0)
	s_barrier
; #define PG8_STAGE(bufoff, gbase, voff) do { _Pragma("unroll") for (int _i = 0; _i < 2; ++_i) \
;         __builtin_amdgcn_global_load_lds((const unsigned*)((const char*)(gbase) + (voff)[_i]), (PG8_LAS unsigned*)(lds + (bufoff) + ldsw + _i * 8192), 16, 0, 0); } while (0)
; #define PG8_LDA(dst, b, h) do { _Pragma("unroll") for (int m = 0; m < 4; ++m) _Pragma("unroll") for (int k = 0; k < 2; ++k) dst[m][k] = *(const PG8_LAS bf16x8*)(lds + PG8_SA(b, h) + aoff + m * 2048 + k * 1024); } while (0)
; #define PG8_MMA(ai, bj, At, Bt) do { __builtin_amdgcn_s_setprio(1); _Pragma("unroll") for (int m = 0; m < 4; ++m) _Pragma("unroll") for (int n = 0; n < 2; ++n) _Pragma("unroll") for (int k = 0; k < 2; ++k) \
;         acc[ai][bj][m][n] = __builtin_amdgcn_mfma_f32_16x16x32_bf16(Bt[n][k], At[m][k], acc[ai][bj][m][n], 0, 0, 0); __builtin_amdgcn_s_setprio(0); } while (0)
; #define PG8_WAIT_V(n) asm volatile("s_waitcnt vmcnt(" #n ")" ::: "memory")
; #define PG8_WAIT_L(n) asm volatile("s_waitcnt lgkmcnt(" #n ")" ::: "memory")
; #define PG8_BAR __builtin_amdgcn_s_barrier()
; #define PG8_SCHED __builtin_amdgcn_sched_barrier(0)
; template <class Epi, class Sched, bool ALIGN_EPI = false, bool SP2 = false>
; __device__ __forceinline__ void gemm_phase(PG8_LAS unsigned char* lds, const Gemm g, const Sched& S, const Epi& E) {
;     ...
;             PG8_WAIT_V(8); PG8_WAIT_L(0); PG8_BAR; PG8_MMA(0, 0, At, B0); PG8_MMA(0, 1, At, B1); PG8_BAR; PG8_SCHED;
;             PG8_LDA(At, 1, 1); PG8_STAGE(PG8_SB(1, 0), b3, voffB); PG8_STAGE(PG8_SB(1, 1), b3 + hstep, voffB); PG8_STAGE(PG8_SA(1, 0), a3, voffA);
;             PG8_WAIT_V(8); PG8_WAIT_L(0); PG8_BAR; PG8_MMA(1, 0, At, B0); PG8_MMA(1, 1, At, B1); PG8_BAR; PG8_SCHED;
	s_setprio 1
	s_waitcnt lgkmcnt(0)
	v_mfma_f32_16x16x32_bf16 v[124:127], v[128:131], v[184:187], v[124:127]
	v_mfma_f32_16x16x32_bf16 v[120:123], v[136:139], v[184:187], v[120:123]
	v_mfma_f32_16x16x32_bf16 v[116:119], v[128:131], v[192:195], v[116:119]
	v_mfma_f32_16x16x32_bf16 v[112:115], v[136:139], v[192:195], v[112:115]
	v_mfma_f32_16x16x32_bf16 v[96:99], v[128:131], v[200:203], v[96:99]
	v_mfma_f32_16x16x32_bf16 v[88:91], v[136:139], v[200:203], v[88:91]
	v_mfma_f32_16x16x32_bf16 v[84:87], v[128:131], v[208:211], v[84:87]
	v_mfma_f32_16x16x32_bf16 v[76:79], v[136:139], v[208:211], v[76:79]
	v_mfma_f32_16x16x32_bf16 v[124:127], v[132:135], v[188:191], v[124:127]
	v_mfma_f32_16x16x32_bf16 v[120:123], v[140:143], v[188:191], v[120:123]
	v_mfma_f32_16x16x32_bf16 v[116:119], v[132:135], v[196:199], v[116:119]
	v_mfma_f32_16x16x32_bf16 v[112:115], v[140:143], v[196:199], v[112:115]
	v_mfma_f32_16x16x32_bf16 v[96:99], v[132:135], v[204:207], v[96:99]
	v_mfma_f32_16x16x32_bf16 v[88:91], v[140:143], v[204:207], v[88:91]
	v_mfma_f32_16x16x32_bf16 v[84:87], v[132:135], v[212:215], v[84:87]
	v_mfma_f32_16x16x32_bf16 v[76:79], v[140:143], v[212:215], v[76:79]
	s_setprio 0
	s_setprio 1
	v_mfma_f32_16x16x32_bf16 v[108:111], v[160:163], v[184:187], v[108:111]
	v_mfma_f32_16x16x32_bf16 v[104:107], v[176:179], v[184:187], v[104:107]
	v_mfma_f32_16x16x32_bf16 v[100:103], v[160:163], v[192:195], v[100:103]
	v_mfma_f32_16x16x32_bf16 v[92:95], v[176:179], v[192:195], v[92:95]
	v_mfma_f32_16x16x32_bf16 v[80:83], v[160:163], v[200:203], v[80:83]
	v_mfma_f32_16x16x32_bf16 v[72:75], v[176:179], v[200:203], v[72:75]
	v_mfma_f32_16x16x32_bf16 v[68:71], v[160:163], v[208:211], v[68:71]
	v_mfma_f32_16x16x32_bf16 v[64:67], v[176:179], v[208:211], v[64:67]
	v_mfma_f32_16x16x32_bf16 v[108:111], v[172:175], v[188:191], v[108:111]
	v_mfma_f32_16x16x32_bf16 v[104:107], v[180:183], v[188:191], v[104:107]
	v_mfma_f32_16x16x32_bf16 v[100:103], v[172:175], v[196:199], v[100:103]
	v_mfma_f32_16x16x32_bf16 v[92:95], v[180:183], v[196:199], v[92:95]
	v_mfma_f32_16x16x32_bf16 v[80:83], v[172:175], v[204:207], v[80:83]
	v_mfma_f32_16x16x32_bf16 v[72:75], v[180:183], v[204:207], v[72:75]
	v_mfma_f32_16x16x32_bf16 v[68:71], v[172:175], v[212:215], v[68:71]
	v_mfma_f32_16x16x32_bf16 v[64:67], v[180:183], v[212:215], v[64:67]
	s_setprio 0
	s_barrier
	s_add_i32 s40, s68, s45
	v_lshl_add_u64 v[164:165], v[164:165], 0, s[6:7]
	s_mov_b32 m0, s40
	ds_read_b128 v[184:187], v171 offset:49152
	ds_read_b128 v[188:191], v171 offset:50176
	ds_read_b128 v[192:195], v171 offset:51200
	ds_read_b128 v[196:199], v171 offset:52224
	ds_read_b128 v[200:203], v171 offset:53248
	ds_read_b128 v[204:207], v171 offset:54272
	ds_read_b128 v[208:211], v171 offset:55296
	ds_read_b128 v[212:215], v171 offset:56320
	global_load_lds_dwordx4 v[164:165], off
	s_add_i32 m0, s40, 0x2000
	s_add_u32 s38, s38, 0x40080
	v_lshl_add_u64 v[164:165], v[216:217], 0, s[6:7]
	s_addc_u32 s39, s39, 0
	s_add_i32 s40, s69, s45
	global_load_lds_dwordx4 v[164:165], off
	v_lshl_add_u64 v[164:165], s[38:39], 0, v[146:147]
	s_mov_b32 m0, s40
	s_nop 0
	global_load_lds_dwordx4 v[164:165], off
	v_lshl_add_u64 v[164:165], s[38:39], 0, v[150:151]
	s_add_i32 m0, s40, 0x2000
	s_nop 0
	global_load_lds_dwordx4 v[164:165], off
	v_lshl_add_u64 v[164:165], v[218:219], 0, s[6:7]
	s_mov_b32 m0, s56
	s_nop 0
	global_load_lds_dwordx4 v[164:165], off
	v_lshl_add_u64 v[164:165], v[220:221], 0, s[6:7]
	s_mov_b32 m0, s57
	s_nop 0
	global_load_lds_dwordx4 v[164:165], off
	s_waitcnt vmcnt(8)
	s_waitcnt lgkmcnt(0)
	s_barrier
	s_setprio 1
	s_waitcnt lgkmcnt(0)
	v_mfma_f32_16x16x32_bf16 v[60:63], v[128:131], v[184:187], v[60:63]
	v_mfma_f32_16x16x32_bf16 v[56:59], v[136:139], v[184:187], v[56:59]
	v_mfma_f32_16x16x32_bf16 v[52:55], v[128:131], v[192:195], v[52:55]
	v_mfma_f32_16x16x32_bf16 v[48:51], v[136:139], v[192:195], v[48:51]
	v_mfma_f32_16x16x32_bf16 v[36:39], v[128:131], v[200:203], v[36:39]
	v_mfma_f32_16x16x32_bf16 v[24:27], v[136:139], v[200:203], v[24:27]
	v_mfma_f32_16x16x32_bf16 v[20:23], v[128:131], v[208:211], v[20:23]
	v_mfma_f32_16x16x32_bf16 v[12:15], v[136:139], v[208:211], v[12:15]
	v_mfma_f32_16x16x32_bf16 v[60:63], v[132:135], v[188:191], v[60:63]
	v_mfma_f32_16x16x32_bf16 v[56:59], v[140:143], v[188:191], v[56:59]
	v_mfma_f32_16x16x32_bf16 v[52:55], v[132:135], v[196:199], v[52:55]
	v_mfma_f32_16x16x32_bf16 v[48:51], v[140:143], v[196:199], v[48:51]
	v_mfma_f32_16x16x32_bf16 v[36:39], v[132:135], v[204:207], v[36:39]
	v_mfma_f32_16x16x32_bf16 v[24:27], v[140:143], v[204:207], v[24:27]
	v_mfma_f32_16x16x32_bf16 v[20:23], v[132:135], v[212:215], v[20:23]
	v_mfma_f32_16x16x32_bf16 v[12:15], v[140:143], v[212:215], v[12:15]
	s_setprio 0
	s_setprio 1
	v_mfma_f32_16x16x32_bf16 v[44:47], v[160:163], v[184:187], v[44:47]
	v_mfma_f32_16x16x32_bf16 v[40:43], v[176:179], v[184:187], v[40:43]
	v_mfma_f32_16x16x32_bf16 v[32:35], v[160:163], v[192:195], v[32:35]
	v_mfma_f32_16x16x32_bf16 v[28:31], v[176:179], v[192:195], v[28:31]
	v_mfma_f32_16x16x32_bf16 v[16:19], v[160:163], v[200:203], v[16:19]
	v_mfma_f32_16x16x32_bf16 v[8:11], v[176:179], v[200:203], v[8:11]
	v_mfma_f32_16x16x32_bf16 v[4:7], v[160:163], v[208:211], v[4:7]
	v_mfma_f32_16x16x32_bf16 v[0:3], v[176:179], v[208:211], v[0:3]
	v_mfma_f32_16x16x32_bf16 v[44:47], v[172:175], v[188:191], v[44:47]
	v_mfma_f32_16x16x32_bf16 v[40:43], v[180:183], v[188:191], v[40:43]
	v_mfma_f32_16x16x32_bf16 v[32:35], v[172:175], v[196:199], v[32:35]
	v_mfma_f32_16x16x32_bf16 v[28:31], v[180:183], v[196:199], v[28:31]
	v_mfma_f32_16x16x32_bf16 v[16:19], v[172:175], v[204:207], v[16:19]
	v_mfma_f32_16x16x32_bf16 v[8:11], v[180:183], v[204:207], v[8:11]
	v_mfma_f32_16x16x32_bf16 v[4:7], v[172:175], v[212:215], v[4:7]
	v_mfma_f32_16x16x32_bf16 v[0:3], v[180:183], v[212:215], v[0:3]
	s_setprio 0
	s_barrier
	s_add_i32 s65, s65, 2
	s_add_u32 s34, s34, 0x100
	s_addc_u32 s35, s35, 0
	s_add_u32 s63, s63, 0x100
	s_addc_u32 s64, s64, 0
	s_branch .LBB0_457
